# stagger blocks with id bit 3 at the start of SwiGLU (1 sleep) and FFN-down (5 sleeps) GEMM phases, as the in-proj phase already does
# baseline (speedup 1.0000x reference)
.LBB0_111:
	s_and_b64 vcc, exec, s[14:15]
	s_cbranch_vccz .LBB0_139
	v_readlane_b32 s98, v255, 18
	s_bitcmp0_b32 s98, 3
	s_cbranch_scc1 .Lstag_skip_res
	s_sleep 0x7f
	s_sleep 0x7f
	s_sleep 0x7f
	s_sleep 0x7f
	s_sleep 0x7f
.Lstag_skip_res:
	s_cmp_eq_u32 s13, 2
	s_cselect_b64 s[16:17], -1, 0
	v_readlane_b32 s4, v255, 16
	s_and_b64 vcc, exec, s[16:17]
	v_readlane_b32 s5, v255, 17
	s_cbranch_vccnz .LBB0_114
	s_load_dwordx4 s[40:43], s[0:1], 0xf8
	s_waitcnt lgkmcnt(0)
	s_mov_b64 s[4:5], s[40:41]

.LBB0_139:
	s_and_b64 vcc, exec, s[8:9]
	s_cbranch_vccz .LBB0_152
	v_readlane_b32 s98, v255, 18
	s_bitcmp0_b32 s98, 3
	s_cbranch_scc1 .Lstag_skip_sw
	s_sleep 0x7f
.Lstag_skip_sw:
	s_mov_b32 s35, s46
	s_mov_b32 s37, s87
	s_waitcnt vmcnt(0)
	v_mov_b32_e32 v8, v228
	s_cmpk_gt_i32 s37, 0xaff
	v_readfirstlane_b32 s48, v8
	s_cbranch_scc1 .LBB0_152
	v_lshlrev_b32_e32 v0, 4, v8
	v_add_u32_e32 v1, 0x2000, v0
	v_ashrrev_i32_e32 v2, 31, v1
	v_lshrrev_b32_e32 v2, 22, v2
	v_add_u32_e32 v2, v1, v2
	v_ashrrev_i32_e32 v9, 10, v2
	v_mul_i32_i24_e32 v2, 0x400, v9
	v_sub_u32_e32 v1, v1, v2
	v_lshrrev_b32_e32 v2, 4, v1
	v_bitop3_b32 v1, v2, v1, 32 bitop3:0x6c
	v_ashrrev_i32_e32 v2, 31, v1
	v_lshrrev_b32_e32 v2, 26, v2
	v_add_u32_e32 v2, v1, v2
	v_lshlrev_b32_e32 v3, 3, v9
	v_ashrrev_i32_e32 v10, 6, v2
	v_and_b32_e32 v3, -16, v3
	v_add_u32_e32 v3, v10, v3
	v_and_b32_e32 v4, 3, v10
	s_mov_b32 s8, 0x1fffe0
	v_lshrrev_b32_e32 v5, 2, v3
	v_lshlrev_b32_e32 v6, 1, v3
	v_and_b32_e32 v2, 0xc0, v2
	v_and_or_b32 v4, v3, s8, v4
	v_and_b32_e32 v5, 4, v5
	v_and_b32_e32 v6, 24, v6
	v_sub_u32_e32 v1, v1, v2
	v_or3_b32 v4, v4, v5, v6
	v_lshlrev_b32_e32 v5, 5, v9
	v_ashrrev_i16_sdwa v1, v230, sext(v1) dst_sel:DWORD dst_unused:UNUSED_PAD src0_sel:DWORD src1_sel:BYTE_0
	v_and_b32_e32 v5, 32, v5
	v_bfe_i32 v11, v1, 0, 16
	v_add_lshl_u32 v1, v5, v11, 1
	v_lshl_add_u32 v130, v4, 11, v1
	v_lshl_add_u32 v132, v3, 11, v1
	v_bfe_i32 v1, v8, 27, 1
	v_lshrrev_b32_e32 v1, 22, v1
	v_add_u32_e32 v1, v0, v1
	v_and_b32_e32 v1, 0xfffffc00, v1
	v_sub_u32_e32 v0, v0, v1
	v_lshrrev_b32_e32 v1, 4, v0
	v_bitop3_b32 v1, v1, v0, 32 bitop3:0x6c
	v_ashrrev_i32_e32 v0, 31, v0
	v_lshrrev_b32_e32 v0, 26, v0
	v_add_u32_e32 v0, v1, v0
	v_ashrrev_i32_e32 v12, 6, v0
	v_ashrrev_i32_e32 v0, 31, v8
	v_lshrrev_b32_e32 v0, 26, v0
	v_add_u32_e32 v0, v8, v0
	s_cmp_eq_u32 s13, 1
	v_ashrrev_i32_e32 v13, 6, v0
	s_cselect_b32 s2, 0, 0x2800000
	v_lshlrev_b32_e32 v0, 3, v13
	s_add_u32 s49, s44, s2
	v_and_b32_e32 v0, -16, v0
	s_addc_u32 s50, s45, 0
	v_add_u32_e32 v0, v12, v0
	v_and_b32_e32 v2, 3, v12
	s_ashr_i32 s52, s37, 31
	v_and_or_b32 v2, v0, s8, v2
	s_lshr_b32 s8, s52, 29
	s_add_i32 s8, s37, s8
	s_ashr_i32 s2, s48, 6
	s_ashr_i32 s12, s8, 3
	s_and_b32 s8, s8, -8
	s_ashr_i32 s9, s48, 8
	s_lshl_b32 s51, s2, 10
	s_sub_i32 s8, s37, s8
	s_cmp_lt_i32 s8, 0
	s_movk_i32 s14, 0x161
	s_cselect_b32 s14, s14, 0x160
	s_mul_i32 s8, s14, s8
	s_add_i32 s8, s8, s12
	s_mul_hi_i32 s12, s8, 0x2e8ba2e9
	s_lshr_b32 s14, s12, 31
	s_ashr_i32 s12, s12, 5
	s_add_i32 s12, s12, s14
	s_lshl_b32 s14, s12, 3
	s_mulk_i32 s12, 0xb0
	s_sub_i32 s12, s8, s12
	s_bfe_u32 s8, s12, 0x3001c
	s_add_i32 s15, s12, s8
	s_sext_i32_i16 s8, s15
	s_and_b32 s15, s15, 0xfff8
	v_lshrrev_b32_e32 v3, 2, v0
	v_lshlrev_b32_e32 v4, 1, v0
	s_sub_i32 s12, s12, s15
	v_and_b32_e32 v3, 4, v3
	v_and_b32_e32 v4, 24, v4
	s_sext_i32_i16 s12, s12
	v_or3_b32 v2, v2, v3, v4
	v_mul_i32_i24_e32 v4, 64, v12
	s_lshr_b32 s8, s8, 3
	s_add_i32 s14, s14, s12
	v_sub_u32_e32 v1, v1, v4
	s_ashr_i32 s15, s14, 31
	s_bfe_i64 s[16:17], s[8:9], 0x100000
	v_lshlrev_b32_e32 v3, 5, v13
	v_ashrrev_i16_sdwa v1, v230, sext(v1) dst_sel:DWORD dst_unused:UNUSED_PAD src0_sel:DWORD src1_sel:BYTE_0
	s_lshl_b64 s[18:19], s[14:15], 19
	s_lshl_b64 s[16:17], s[16:17], 19
	v_and_b32_e32 v3, 32, v3
	v_bfe_i32 v14, v1, 0, 16
	s_add_u32 s16, s49, s16
	v_add_lshl_u32 v1, v3, v14, 1
	s_addc_u32 s17, s50, s17
	s_add_i32 s15, s51, 0
	v_lshl_add_u32 v16, v2, 11, v1
	s_add_i32 m0, s15, 0x10000
	v_lshl_add_u32 v134, v0, 11, v1
	global_load_lds_dwordx4 v16, s[16:17]
	s_add_i32 m0, s15, 0x12000
	s_add_u32 s18, s30, s18
	global_load_lds_dwordx4 v130, s[16:17]
	s_addc_u32 s19, s31, s19
	s_mov_b32 m0, s15
	s_add_i32 s54, s15, 0x2000
	global_load_lds_dwordx4 v134, s[18:19]
	s_mov_b32 m0, s54
	s_add_u32 s22, s16, 0x40000
	global_load_lds_dwordx4 v132, s[18:19]
	s_addc_u32 s23, s17, 0
	s_add_i32 m0, s15, 0x14000
	v_mov_b32_e32 v131, v17
	global_load_lds_dwordx4 v16, s[22:23]
	s_add_i32 m0, s15, 0x16000
	v_mov_b32_e32 v135, v17
	global_load_lds_dwordx4 v130, s[22:23]
	s_add_u32 s22, s18, 0x40000
	s_addc_u32 s23, s19, 0
	s_add_i32 s55, s15, 0x4000
	s_mov_b32 m0, s55
	s_add_i32 s56, s15, 0x6000
	global_load_lds_dwordx4 v134, s[22:23]
	s_mov_b32 m0, s56
	v_mov_b32_e32 v133, v17
	global_load_lds_dwordx4 v132, s[22:23]
	v_lshl_add_u64 v[6:7], s[16:17], 0, v[16:17]
	v_lshl_add_u64 v[4:5], s[16:17], 0, v[130:131]
	v_lshl_add_u64 v[2:3], s[18:19], 0, v[134:135]
	s_cmp_lg_u32 s9, 1
	v_lshl_add_u64 v[0:1], s[18:19], 0, v[132:133]
	s_cbranch_scc1 .LBB0_143
	s_barrier
